# strategy 8 on stick-breaking tiles A and B: the 8 V^T fragment LDS reads issued right after the QK MFMAs into the just-consumed K-fragment registers, PV MFMAs no longer wait on LDS one by one
# speedup vs baseline: 1.0118x; 1.0118x over previous
.LBB0_632:
	s_add_i32 s0, s29, 6
	s_max_i32 s18, s0, 0
	s_lshl_b64 s[0:1], s[18:19], 5
	v_or_b32_e32 v0, s0, v212
	v_mad_u64_u32 v[0:1], s[30:31], v0, s78, v[228:229]
	v_mad_u32_u24 v1, s1, v242, v1
	global_load_dwordx4 v[188:191], v[0:1], off offset:2048
	global_load_dwordx4 v[184:187], v[0:1], off offset:2080
	global_load_dwordx4 v[180:183], v[0:1], off offset:2112
	global_load_dwordx4 v[176:179], v[0:1], off offset:2144
	v_or_b32_e32 v0, s0, v214
	v_mad_u64_u32 v[16:17], s[30:31], v0, s78, v[230:231]
	v_or_b32_e32 v18, s0, v216
	v_mad_u32_u24 v17, s1, v242, v17
	v_mad_u64_u32 v[18:19], s[30:31], v18, s78, v[230:231]
	v_mad_u32_u24 v19, s1, v242, v19
	global_load_dwordx4 v[192:195], v[16:17], off
	global_load_dwordx4 v[196:199], v[18:19], off
	v_or_b32_e32 v16, s0, v218
	v_mad_u64_u32 v[16:17], s[30:31], v16, s78, v[230:231]
	v_or_b32_e32 v18, s0, v220
	v_mad_u32_u24 v17, s1, v242, v17
	v_mad_u64_u32 v[18:19], s[30:31], v18, s78, v[230:231]
	v_mad_u32_u24 v19, s1, v242, v19
	global_load_dwordx4 v[204:207], v[16:17], off
	global_load_dwordx4 v[200:203], v[18:19], off
	s_waitcnt vmcnt(0)
	v_mfma_f32_32x32x16_bf16 v[0:15], v[124:127], v[96:99], 0
	s_waitcnt lgkmcnt(0)
	s_add_i32 s82, s36, s48
	s_add_i32 s0, s82, 0x11f
	s_cmp_lt_i32 s0, s39
	ds_write_b128 v211, v[132:135]
	ds_write_b128 v211, v[140:143] offset:512
	ds_write_b128 v211, v[152:155] offset:1024
	ds_write_b128 v211, v[148:151] offset:1536
	v_mfma_f32_32x32x16_bf16 v[0:15], v[120:123], v[100:103], v[0:15]
	v_mfma_f32_32x32x16_bf16 v[0:15], v[116:119], v[104:107], v[0:15]
	v_mfma_f32_32x32x16_bf16 v[0:15], v[112:115], v[108:111], v[0:15]
	ds_read_b64_tr_b16 v[124:125], v213
	ds_read_b64_tr_b16 v[126:127], v213 offset:512
	ds_read_b64_tr_b16 v[120:121], v213 offset:1024
	ds_read_b64_tr_b16 v[122:123], v213 offset:1536
	ds_read_b64_tr_b16 v[116:117], v213 offset:2048
	ds_read_b64_tr_b16 v[118:119], v213 offset:2560
	ds_read_b64_tr_b16 v[112:113], v213 offset:3072
	ds_read_b64_tr_b16 v[114:115], v213 offset:3584
	s_nop 11
	v_mul_f32_e32 v12, 0xbe38aa3b, v12
	v_min_f32_e32 v12, 0x42c80000, v12
	v_mul_f32_e32 v0, 0xbe38aa3b, v0
	v_mul_f32_e32 v2, 0xbe38aa3b, v2
	v_mul_f32_e32 v4, 0xbe38aa3b, v4
	v_mul_f32_e32 v6, 0xbe38aa3b, v6
	v_mul_f32_e32 v8, 0xbe38aa3b, v8
	v_mul_f32_e32 v10, 0xbe38aa3b, v10
	v_exp_f32_e32 v64, v12
	v_mul_f32_e32 v12, 0xbe38aa3b, v13
	v_mul_f32_e32 v13, 0xbe38aa3b, v14
	v_min_f32_e32 v0, 0x42c80000, v0
	v_min_f32_e32 v2, 0x42c80000, v2
	v_min_f32_e32 v4, 0x42c80000, v4
	v_min_f32_e32 v6, 0x42c80000, v6
	v_min_f32_e32 v8, 0x42c80000, v8
	v_min_f32_e32 v10, 0x42c80000, v10
	v_min_f32_e32 v12, 0x42c80000, v12
	v_min_f32_e32 v13, 0x42c80000, v13
	v_exp_f32_e32 v16, v0
	v_mul_f32_e32 v0, 0xbe38aa3b, v1
	v_exp_f32_e32 v18, v2
	v_mul_f32_e32 v2, 0xbe38aa3b, v3
	v_exp_f32_e32 v22, v4
	v_mul_f32_e32 v4, 0xbe38aa3b, v5
	v_exp_f32_e32 v24, v6
	v_mul_f32_e32 v6, 0xbe38aa3b, v7
	v_exp_f32_e32 v28, v8
	v_mul_f32_e32 v8, 0xbe38aa3b, v9
	v_exp_f32_e32 v30, v10
	v_mul_f32_e32 v10, 0xbe38aa3b, v11
	v_exp_f32_e32 v65, v12
	v_exp_f32_e32 v66, v13
	v_mul_f32_e32 v13, 0xbe38aa3b, v15
	v_min_f32_e32 v0, 0x42c80000, v0
	v_min_f32_e32 v2, 0x42c80000, v2
	v_min_f32_e32 v4, 0x42c80000, v4
	v_min_f32_e32 v6, 0x42c80000, v6
	v_min_f32_e32 v8, 0x42c80000, v8
	v_min_f32_e32 v10, 0x42c80000, v10
	v_min_f32_e32 v13, 0x42c80000, v13
	v_exp_f32_e32 v17, v0
	v_exp_f32_e32 v19, v2
	v_exp_f32_e32 v23, v4
	v_exp_f32_e32 v25, v6
	v_exp_f32_e32 v29, v8
	v_exp_f32_e32 v31, v10
	v_exp_f32_e32 v67, v13
	v_add_f32_e32 v12, 1.0, v64
	v_rcp_f32_e32 v20, v12
	v_add_f32_e32 v12, 1.0, v65
	v_rcp_f32_e32 v21, v12
	v_add_f32_e32 v12, 1.0, v66
	v_add_f32_e32 v0, 1.0, v16
	v_add_f32_e32 v1, 1.0, v17
	v_add_f32_e32 v2, 1.0, v18
	v_add_f32_e32 v3, 1.0, v19
	v_add_f32_e32 v4, 1.0, v22
	v_add_f32_e32 v5, 1.0, v23
	v_add_f32_e32 v6, 1.0, v24
	v_add_f32_e32 v7, 1.0, v25
	v_add_f32_e32 v8, 1.0, v28
	v_add_f32_e32 v9, 1.0, v29
	v_add_f32_e32 v10, 1.0, v30
	v_add_f32_e32 v11, 1.0, v31
	v_rcp_f32_e32 v26, v12
	v_add_f32_e32 v12, 1.0, v67
	v_rcp_f32_e32 v0, v0
	v_rcp_f32_e32 v1, v1
	v_rcp_f32_e32 v2, v2
	v_rcp_f32_e32 v3, v3
	v_rcp_f32_e32 v4, v4
	v_rcp_f32_e32 v5, v5
	v_rcp_f32_e32 v6, v6
	v_rcp_f32_e32 v7, v7
	v_rcp_f32_e32 v8, v8
	v_rcp_f32_e32 v9, v9
	v_rcp_f32_e32 v10, v10
	v_rcp_f32_e32 v11, v11
	v_rcp_f32_e32 v27, v12
	v_pk_mul_f32 v[12:13], v[16:17], v[0:1]
	v_pk_mul_f32 v[14:15], v[18:19], v[2:3]
	v_pk_mul_f32 v[16:17], v[22:23], v[4:5]
	v_pk_mul_f32 v[18:19], v[24:25], v[6:7]
	v_pk_mul_f32 v[22:23], v[28:29], v[8:9]
	v_pk_mul_f32 v[24:25], v[30:31], v[10:11]
	v_pk_mul_f32 v[28:29], v[64:65], v[20:21]
	v_pk_mul_f32 v[30:31], v[66:67], v[26:27]
	s_cbranch_scc1 .LBB0_634
; __device__ __forceinline__ s16x4 vtr(lds_cptr p) { return __builtin_bit_cast(s16x4, __builtin_amdgcn_ds_read_tr16_b64_v4i16((ATT_LAS s16x4*)p)); }
; __device__ __forceinline__ bf16x8 cat8(s16x4 lo, s16x4 hi) { return (bf16x8){lo[0], lo[1], lo[2], lo[3], hi[0], hi[1], hi[2], hi[3]}; }
; template <int KEYS> __device__ __forceinline__ void pv_tile(f32x16 (&o)[2], lds_cptr vbase, const bf16x8 (&pf)[KEYS / 16], int lane) {
;     const int hi = lane >> 5, li = lane & 15;
;     lds_cptr vp = vbase + (4 * hi + (li >> 2)) * 64 + ((lane >> 4) & 1) * 32 + (lane & 3) * 8;
; #pragma unroll
;     for (int d0 = 0; d0 < 2; ++d0)
; #pragma unroll
;         for (int ks = 0; ks < KEYS / 16; ++ks) {
;             const s16x4 lo = vtr(vp + d0 * (KEYS * 64) + ks * 1024), hh = vtr(vp + d0 * (KEYS * 64) + ks * 1024 + 512);
;             o[d0] = __builtin_amdgcn_mfma_f32_32x32x16_bf16(cat8(lo, hh), pf[ks], o[d0], 0, 0, 0);
;         }
; }
	v_add_u32_e32 v64, s48, v215
	v_add_u32_e32 v65, 0x100, v64
	v_cmp_lt_i32_e32 vcc, v65, v234
	v_add_u32_e32 v65, 0x101, v64
	v_cmp_lt_i32_e64 s[0:1], v65, v234
	v_add_u32_e32 v65, 0x102, v64
	v_cmp_lt_i32_e64 s[42:43], v65, v234
	v_add_u32_e32 v65, 0x103, v64
	v_cmp_lt_i32_e64 s[44:45], v65, v234
	v_add_u32_e32 v65, 0x108, v64
	v_cmp_lt_i32_e64 s[50:51], v65, v234
	v_add_u32_e32 v65, 0x109, v64
	v_cmp_lt_i32_e64 s[52:53], v65, v234
	v_add_u32_e32 v65, 0x10a, v64
	v_cmp_lt_i32_e64 s[54:55], v65, v234
	v_add_u32_e32 v65, 0x10b, v64
	v_cmp_lt_i32_e64 s[56:57], v65, v234
	v_add_u32_e32 v65, 0x110, v64
	v_cmp_lt_i32_e64 s[58:59], v65, v234
	v_add_u32_e32 v65, 0x111, v64
	v_cmp_lt_i32_e64 s[60:61], v65, v234
	v_add_u32_e32 v65, 0x112, v64
	v_cmp_lt_i32_e64 s[62:63], v65, v234
	v_add_u32_e32 v65, 0x113, v64
	v_cmp_lt_i32_e64 s[64:65], v65, v234
	v_add_u32_e32 v65, 0x118, v64
	v_cmp_lt_i32_e64 s[66:67], v65, v234
	v_add_u32_e32 v65, 0x119, v64
	v_cmp_lt_i32_e64 s[68:69], v65, v234
	v_add_u32_e32 v65, 0x11a, v64
	v_add_u32_e32 v64, 0x11b, v64
	v_cmp_lt_i32_e64 s[70:71], v65, v234
	v_cmp_lt_i32_e64 s[72:73], v64, v234
	s_or_b64 s[70:71], s[72:73], s[70:71]
	s_or_b64 s[68:69], s[70:71], s[68:69]
	s_or_b64 s[66:67], s[68:69], s[66:67]
	s_or_b64 s[64:65], s[66:67], s[64:65]
	s_or_b64 s[62:63], s[64:65], s[62:63]
	s_or_b64 s[60:61], s[62:63], s[60:61]
	s_or_b64 s[58:59], s[60:61], s[58:59]
	s_or_b64 s[56:57], s[58:59], s[56:57]
	s_or_b64 s[54:55], s[56:57], s[54:55]
	s_or_b64 s[52:53], s[54:55], s[52:53]
	s_or_b64 s[50:51], s[52:53], s[50:51]
	s_or_b64 s[44:45], s[50:51], s[44:45]
	s_or_b64 s[42:43], s[44:45], s[42:43]
	s_or_b64 s[0:1], s[42:43], s[0:1]
	s_or_b64 vcc, s[0:1], vcc
	v_cndmask_b32_e64 v27, 0, v27, s[72:73]
	v_cndmask_b32_e64 v26, 0, v26, s[70:71]
	v_cndmask_b32_e64 v21, 0, v21, s[68:69]
	v_cndmask_b32_e64 v20, 0, v20, s[66:67]
	v_cndmask_b32_e64 v11, 0, v11, s[64:65]
	v_cndmask_b32_e64 v10, 0, v10, s[62:63]
	v_cndmask_b32_e64 v9, 0, v9, s[60:61]
	v_cndmask_b32_e64 v8, 0, v8, s[58:59]
	v_cndmask_b32_e64 v7, 0, v7, s[56:57]
	v_cndmask_b32_e64 v6, 0, v6, s[54:55]
	v_cndmask_b32_e64 v5, 0, v5, s[52:53]
	v_cndmask_b32_e64 v4, 0, v4, s[50:51]
	v_cndmask_b32_e64 v3, 0, v3, s[44:45]
	v_cndmask_b32_e64 v2, 0, v2, s[42:43]
	v_cndmask_b32_e64 v1, 0, v1, s[0:1]
	v_cndmask_b32_e32 v0, 0, v0, vcc
	v_cndmask_b32_e32 v12, 1.0, v12, vcc
	v_cndmask_b32_e64 v13, 1.0, v13, s[0:1]
	v_cndmask_b32_e64 v14, 1.0, v14, s[42:43]
	v_cndmask_b32_e64 v15, 1.0, v15, s[44:45]
	v_cndmask_b32_e64 v16, 1.0, v16, s[50:51]
	v_cndmask_b32_e64 v17, 1.0, v17, s[52:53]
	v_cndmask_b32_e64 v18, 1.0, v18, s[54:55]
	v_cndmask_b32_e64 v19, 1.0, v19, s[56:57]
	v_cndmask_b32_e64 v22, 1.0, v22, s[58:59]
	v_cndmask_b32_e64 v23, 1.0, v23, s[60:61]
	v_cndmask_b32_e64 v24, 1.0, v24, s[62:63]
	v_cndmask_b32_e64 v25, 1.0, v25, s[64:65]
	v_cndmask_b32_e64 v28, 1.0, v28, s[66:67]
	v_cndmask_b32_e64 v29, 1.0, v29, s[68:69]
	v_cndmask_b32_e64 v30, 1.0, v30, s[70:71]
	v_cndmask_b32_e64 v31, 1.0, v31, s[72:73]
.LBB0_634:
	v_mov_b32_e32 v64, v13
	v_mov_b32_e32 v65, v14
	v_mov_b32_e32 v66, v12
	v_mov_b32_e32 v67, v15
	v_pk_mul_f32 v[64:65], v[64:65], v[66:67]
	v_mov_b32_e32 v66, v17
	v_mov_b32_e32 v67, v18
	v_mov_b32_e32 v68, v16
	v_mov_b32_e32 v69, v19
	v_pk_mul_f32 v[66:67], v[66:67], v[68:69]
	v_mov_b32_e32 v68, v23
	v_mov_b32_e32 v69, v24
	v_mov_b32_e32 v70, v22
	v_mov_b32_e32 v71, v25
	v_mul_f32_e32 v64, v64, v65
	v_pk_mul_f32 v[68:69], v[68:69], v[70:71]
	v_mov_b32_e32 v70, v29
	v_mov_b32_e32 v71, v30
	v_mov_b32_e32 v72, v28
	v_mov_b32_e32 v73, v31
	v_pk_mul_f32 v[70:71], v[70:71], v[72:73]
	v_mov_b32_e32 v12, v64
	v_mov_b32_e32 v16, v64
	v_pk_mul_f32 v[70:71], v[70:71], v[70:71] op_sel:[0,1] op_sel_hi:[1,0]
	s_nop 0
	v_permlane32_swap_b32_e32 v12, v16
	v_cndmask_b32_e64 v65, v12, v16, s[40:41]
	v_mov_b32_e32 v12, v70
	v_mov_b32_e32 v16, v70
	s_nop 1
	v_permlane32_swap_b32_e32 v12, v16
	v_cndmask_b32_e64 v71, v12, v16, s[40:41]
	v_cndmask_b32_e64 v12, 1.0, v71, s[40:41]
	v_mul_f32_e32 v12, v237, v12
	v_mul_f32_e32 v16, v31, v12
	v_mul_f32_e32 v22, v30, v16
	v_mul_f32_e32 v28, v29, v22
	v_mul_f32_e32 v12, v27, v12
	v_mul_f32_e32 v22, v21, v22
	v_mul_f32_e32 v27, v20, v28
	v_mov_b32_e32 v20, v68
	v_mov_b32_e32 v21, v70
	v_mov_b32_e32 v70, v69
	v_pk_mul_f32 v[20:21], v[20:21], v[70:71]
	v_mul_f32_e32 v26, v26, v16
	v_mov_b32_e32 v16, v20
	v_mov_b32_e32 v28, v20
	s_nop 1
	v_permlane32_swap_b32_e32 v16, v28
	v_cndmask_b32_e64 v236, v16, v28, s[40:41]
	v_cndmask_b32_e64 v16, 1.0, v236, s[40:41]
	v_pk_mul_f32 v[20:21], v[20:21], v[236:237]
	s_add_i32 s77, s29, 8
	v_mul_f32_e32 v16, v16, v21
	v_mul_f32_e32 v25, v25, v16
	v_mul_f32_e32 v24, v24, v25
	v_mul_f32_e32 v23, v23, v24
	v_mul_f32_e32 v24, v9, v24
	v_mul_f32_e32 v23, v8, v23
	v_mov_b32_e32 v8, v66
	v_mov_b32_e32 v9, v20
	v_mov_b32_e32 v20, v67
	v_pk_mul_f32 v[8:9], v[8:9], v[20:21]
	v_mul_f32_e32 v11, v11, v16
	v_mov_b32_e32 v16, v8
	v_mov_b32_e32 v20, v8
	s_nop 1
	v_permlane32_swap_b32_e32 v16, v20
	v_cndmask_b32_e64 v16, v16, v20, s[40:41]
	v_mul_f32_e32 v8, v8, v16
	v_cndmask_b32_e64 v20, 1.0, v16, s[40:41]
	v_mul_f32_e32 v66, v8, v9
	v_cndmask_b32_e64 v8, 1.0, v65, s[40:41]
	v_mul_f32_e32 v20, v20, v9
	v_mul_f32_e32 v8, v8, v66
	v_mul_f32_e32 v19, v19, v20
	v_mul_f32_e32 v9, v15, v8
	v_mul_f32_e32 v18, v18, v19
	v_mul_f32_e32 v14, v14, v9
	v_mul_f32_e32 v17, v17, v18
	v_mul_f32_e32 v13, v13, v14
	v_mul_f32_e32 v10, v10, v25
	v_mul_f32_e32 v7, v7, v20
	v_mul_f32_e32 v6, v6, v19
	v_mul_f32_e32 v5, v5, v18
	v_mul_f32_e32 v4, v4, v17
	v_mul_f32_e32 v3, v3, v8
	v_mul_f32_e32 v2, v2, v9
	v_mul_f32_e32 v1, v1, v14
	v_mul_f32_e32 v0, v0, v13
	v_cvt_pk_bf16_f32 v16, v0, v1
	v_cvt_pk_bf16_f32 v17, v2, v3
	v_cvt_pk_bf16_f32 v18, v4, v5
	v_cvt_pk_bf16_f32 v19, v6, v7
	v_cvt_pk_bf16_f32 v68, v23, v24
	v_cvt_pk_bf16_f32 v69, v10, v11
	v_cvt_pk_bf16_f32 v70, v27, v22
	v_cvt_pk_bf16_f32 v71, v26, v12
	s_waitcnt lgkmcnt(0)
	s_nop 1
	v_mfma_f32_32x32x16_bf16 v[32:47], v[124:127], v[16:19], v[32:47]
	s_cmp_lt_i32 s77, 1
	s_nop 10
	v_mov_b64_e32 v[0:1], v[32:33]
	v_mov_b64_e32 v[2:3], v[34:35]
	v_mov_b64_e32 v[4:5], v[36:37]
	v_mov_b64_e32 v[6:7], v[38:39]
	v_mov_b64_e32 v[8:9], v[40:41]
	v_mov_b64_e32 v[10:11], v[42:43]
	v_mov_b64_e32 v[12:13], v[44:45]
	v_mov_b64_e32 v[14:15], v[46:47]
	s_nop 1
	v_mfma_f32_32x32x16_bf16 v[0:15], v[120:123], v[68:71], v[0:15]
	v_mfma_f32_32x32x16_bf16 v[48:63], v[116:119], v[16:19], v[48:63]
	s_nop 11
	v_mov_b64_e32 v[16:17], v[48:49]
	v_mov_b64_e32 v[18:19], v[50:51]
	v_mov_b64_e32 v[20:21], v[52:53]
	v_mov_b64_e32 v[22:23], v[54:55]
	v_mov_b64_e32 v[24:25], v[56:57]
	v_mov_b64_e32 v[26:27], v[58:59]
	v_mov_b64_e32 v[28:29], v[60:61]
	v_mov_b64_e32 v[30:31], v[62:63]
	s_nop 1
	v_mfma_f32_32x32x16_bf16 v[16:31], v[112:115], v[68:71], v[16:31]
	s_cbranch_scc1 .LBB0_629
; #define SBW_LOAD(j, KF, VR) do { const size_t kb_ = (size_t)(j) * 32; \
;         _Pragma("unroll") for (int s = 0; s < 4; ++s) KF[s] = *(const bf16x8*)(K + (kb_ + r32) * ld + s * 16 + hi * 8); \
;         _Pragma("unroll") for (int c4 = 0; c4 < 4; ++c4) VR[c4] = *(const u32x4*)(V + (kb_ + (lane >> 3) + 8 * c4) * ld + (lane & 7) * 8); } while (0)
; __device__ __forceinline__ void sb_wave_unit(const bf16_t* Q, const bf16_t* K, const bf16_t* V, int ld, bf16_t* O, int ldo, int q0, char* wl, int lane) {
;     ...
;         if (j < 1 || !__any(carry > 0.f)) break;
;         SBW_LOAD(SBW_CL(j - 3), kfA, vrA);
;         SBW_TILE(j - 1, kfB, vrB);
	v_mul_f32_e32 v32, v64, v65
	v_mul_f32_e32 v49, v32, v66
	v_cmp_lt_f32_e32 vcc, 0x2000, v49
	s_mov_b64 s[30:31], 0
	s_cbranch_vccz .LBB0_645
	s_add_i32 s1, s29, 5
	s_max_i32 s18, s1, 0
	s_lshl_b64 s[34:35], s[18:19], 5
	v_or_b32_e32 v32, s34, v212
	v_mad_u64_u32 v[32:33], s[42:43], v32, s78, v[228:229]
	v_mad_u32_u24 v33, s35, v242, v33
	global_load_dwordx4 v[124:127], v[32:33], off offset:2048
	global_load_dwordx4 v[120:123], v[32:33], off offset:2080
	global_load_dwordx4 v[116:119], v[32:33], off offset:2112
	global_load_dwordx4 v[112:115], v[32:33], off offset:2144
	v_or_b32_e32 v32, s34, v214
	v_mad_u64_u32 v[50:51], s[42:43], v32, s78, v[230:231]
	v_or_b32_e32 v48, s34, v216
	v_mad_u32_u24 v51, s35, v242, v51
	v_mad_u64_u32 v[52:53], s[42:43], v48, s78, v[230:231]
	v_or_b32_e32 v48, s34, v218
	v_mad_u32_u24 v53, s35, v242, v53
	global_load_dwordx4 v[132:135], v[50:51], off
	global_load_dwordx4 v[140:143], v[52:53], off
	v_mad_u64_u32 v[50:51], s[42:43], v48, s78, v[230:231]
	v_or_b32_e32 v48, s34, v220
	v_mad_u32_u24 v51, s35, v242, v51
	v_mad_u64_u32 v[52:53], s[42:43], v48, s78, v[230:231]
	v_mad_u32_u24 v53, s35, v242, v53
	global_load_dwordx4 v[152:155], v[50:51], off
	global_load_dwordx4 v[148:151], v[52:53], off
	v_mfma_f32_32x32x16_bf16 v[32:47], v[156:159], v[96:99], 0
	s_waitcnt lgkmcnt(0)
	s_add_i32 s0, s82, 0x100
	s_cmp_le_i32 s0, s39
	ds_write_b128 v211, v[164:167]
	ds_write_b128 v211, v[160:163] offset:512
	ds_write_b128 v211, v[172:175] offset:1024
	ds_write_b128 v211, v[168:171] offset:1536
	v_mfma_f32_32x32x16_bf16 v[32:47], v[144:147], v[100:103], v[32:47]
	v_mfma_f32_32x32x16_bf16 v[32:47], v[136:139], v[104:107], v[32:47]
	v_mfma_f32_32x32x16_bf16 v[32:47], v[128:131], v[108:111], v[32:47]
	ds_read_b64_tr_b16 v[156:157], v213
	ds_read_b64_tr_b16 v[158:159], v213 offset:512
	ds_read_b64_tr_b16 v[144:145], v213 offset:1024
	ds_read_b64_tr_b16 v[146:147], v213 offset:1536
	ds_read_b64_tr_b16 v[136:137], v213 offset:2048
	ds_read_b64_tr_b16 v[138:139], v213 offset:2560
	ds_read_b64_tr_b16 v[128:129], v213 offset:3072
	ds_read_b64_tr_b16 v[130:131], v213 offset:3584
	s_nop 11
	v_mul_f32_e32 v44, 0xbe38aa3b, v44
	v_min_f32_e32 v44, 0x42c80000, v44
	v_mul_f32_e32 v32, 0xbe38aa3b, v32
	v_mul_f32_e32 v34, 0xbe38aa3b, v34
	v_mul_f32_e32 v36, 0xbe38aa3b, v36
	v_mul_f32_e32 v38, 0xbe38aa3b, v38
	v_mul_f32_e32 v40, 0xbe38aa3b, v40
	v_mul_f32_e32 v42, 0xbe38aa3b, v42
	v_exp_f32_e32 v66, v44
	v_mul_f32_e32 v44, 0xbe38aa3b, v45
	v_mul_f32_e32 v45, 0xbe38aa3b, v46
	v_min_f32_e32 v32, 0x42c80000, v32
	v_min_f32_e32 v34, 0x42c80000, v34
	v_min_f32_e32 v36, 0x42c80000, v36
	v_min_f32_e32 v38, 0x42c80000, v38
	v_min_f32_e32 v40, 0x42c80000, v40
	v_min_f32_e32 v42, 0x42c80000, v42
	v_min_f32_e32 v44, 0x42c80000, v44
	v_min_f32_e32 v45, 0x42c80000, v45
	v_exp_f32_e32 v50, v32
	v_mul_f32_e32 v32, 0xbe38aa3b, v33
	v_exp_f32_e32 v52, v34
	v_mul_f32_e32 v34, 0xbe38aa3b, v35
	v_exp_f32_e32 v56, v36
	v_mul_f32_e32 v36, 0xbe38aa3b, v37
	v_exp_f32_e32 v58, v38
	v_mul_f32_e32 v38, 0xbe38aa3b, v39
	v_exp_f32_e32 v62, v40
	v_mul_f32_e32 v40, 0xbe38aa3b, v41
	v_exp_f32_e32 v64, v42
	v_mul_f32_e32 v42, 0xbe38aa3b, v43
	v_exp_f32_e32 v67, v44
	v_exp_f32_e32 v68, v45
	v_mul_f32_e32 v45, 0xbe38aa3b, v47
	v_min_f32_e32 v32, 0x42c80000, v32
	v_min_f32_e32 v34, 0x42c80000, v34
	v_min_f32_e32 v36, 0x42c80000, v36
	v_min_f32_e32 v38, 0x42c80000, v38
	v_min_f32_e32 v40, 0x42c80000, v40
	v_min_f32_e32 v42, 0x42c80000, v42
	v_min_f32_e32 v45, 0x42c80000, v45
	v_exp_f32_e32 v51, v32
	v_exp_f32_e32 v53, v34
	v_exp_f32_e32 v57, v36
	v_exp_f32_e32 v59, v38
	v_exp_f32_e32 v63, v40
	v_exp_f32_e32 v65, v42
	v_exp_f32_e32 v69, v45
	v_add_f32_e32 v44, 1.0, v66
	v_rcp_f32_e32 v54, v44
	v_add_f32_e32 v44, 1.0, v67
	v_rcp_f32_e32 v55, v44
	v_add_f32_e32 v44, 1.0, v68
	v_add_f32_e32 v32, 1.0, v50
	v_add_f32_e32 v33, 1.0, v51
	v_add_f32_e32 v34, 1.0, v52
	v_add_f32_e32 v35, 1.0, v53
	v_add_f32_e32 v36, 1.0, v56
	v_add_f32_e32 v37, 1.0, v57
	v_add_f32_e32 v38, 1.0, v58
	v_add_f32_e32 v39, 1.0, v59
	v_add_f32_e32 v40, 1.0, v62
	v_add_f32_e32 v41, 1.0, v63
	v_add_f32_e32 v42, 1.0, v64
	v_add_f32_e32 v43, 1.0, v65
	v_rcp_f32_e32 v60, v44
	v_add_f32_e32 v44, 1.0, v69
	v_rcp_f32_e32 v32, v32
	v_rcp_f32_e32 v33, v33
	v_rcp_f32_e32 v34, v34
	v_rcp_f32_e32 v35, v35
	v_rcp_f32_e32 v36, v36
	v_rcp_f32_e32 v37, v37
	v_rcp_f32_e32 v38, v38
	v_rcp_f32_e32 v39, v39
	v_rcp_f32_e32 v40, v40
	v_rcp_f32_e32 v41, v41
	v_rcp_f32_e32 v42, v42
	v_rcp_f32_e32 v43, v43
	v_rcp_f32_e32 v61, v44
	v_pk_mul_f32 v[44:45], v[50:51], v[32:33]
	v_pk_mul_f32 v[46:47], v[52:53], v[34:35]
	v_pk_mul_f32 v[50:51], v[56:57], v[36:37]
	v_pk_mul_f32 v[52:53], v[58:59], v[38:39]
	v_pk_mul_f32 v[56:57], v[62:63], v[40:41]
	v_pk_mul_f32 v[58:59], v[64:65], v[42:43]
	v_pk_mul_f32 v[62:63], v[66:67], v[54:55]
	v_pk_mul_f32 v[64:65], v[68:69], v[60:61]
	s_cbranch_scc1 .LBB0_638
; __device__ __forceinline__ s16x4 vtr(lds_cptr p) { return __builtin_bit_cast(s16x4, __builtin_amdgcn_ds_read_tr16_b64_v4i16((ATT_LAS s16x4*)p)); }
; __device__ __forceinline__ bf16x8 cat8(s16x4 lo, s16x4 hi) { return (bf16x8){lo[0], lo[1], lo[2], lo[3], hi[0], hi[1], hi[2], hi[3]}; }
; template <int KEYS> __device__ __forceinline__ void pv_tile(f32x16 (&o)[2], lds_cptr vbase, const bf16x8 (&pf)[KEYS / 16], int lane) {
;     const int hi = lane >> 5, li = lane & 15;
;     lds_cptr vp = vbase + (4 * hi + (li >> 2)) * 64 + ((lane >> 4) & 1) * 32 + (lane & 3) * 8;
; #pragma unroll
;     for (int d0 = 0; d0 < 2; ++d0)
; #pragma unroll
;         for (int ks = 0; ks < KEYS / 16; ++ks) {
;             const s16x4 lo = vtr(vp + d0 * (KEYS * 64) + ks * 1024), hh = vtr(vp + d0 * (KEYS * 64) + ks * 1024 + 512);
;             o[d0] = __builtin_amdgcn_mfma_f32_32x32x16_bf16(cat8(lo, hh), pf[ks], o[d0], 0, 0, 0);
;         }
; }
	v_add_u32_e32 v48, s48, v215
	v_add_u32_e32 v66, 0xe0, v48
	v_cmp_lt_i32_e32 vcc, v66, v234
	v_add_u32_e32 v66, 0xe1, v48
	v_cmp_lt_i32_e64 s[0:1], v66, v234
	v_add_u32_e32 v66, 0xe2, v48
	v_cmp_lt_i32_e64 s[42:43], v66, v234
	v_add_u32_e32 v66, 0xe3, v48
	v_cmp_lt_i32_e64 s[44:45], v66, v234
	v_add_u32_e32 v66, 0xe8, v48
	v_cmp_lt_i32_e64 s[50:51], v66, v234
	v_add_u32_e32 v66, 0xe9, v48
	v_cmp_lt_i32_e64 s[52:53], v66, v234
	v_add_u32_e32 v66, 0xea, v48
	v_cmp_lt_i32_e64 s[54:55], v66, v234
	v_add_u32_e32 v66, 0xeb, v48
	v_cmp_lt_i32_e64 s[56:57], v66, v234
	v_add_u32_e32 v66, 0xf0, v48
	v_cmp_lt_i32_e64 s[58:59], v66, v234
	v_add_u32_e32 v66, 0xf1, v48
	v_cmp_lt_i32_e64 s[60:61], v66, v234
	v_add_u32_e32 v66, 0xf2, v48
	v_cmp_lt_i32_e64 s[62:63], v66, v234
	v_add_u32_e32 v66, 0xf3, v48
	v_cmp_lt_i32_e64 s[64:65], v66, v234
	v_add_u32_e32 v66, 0xf8, v48
	v_cmp_lt_i32_e64 s[66:67], v66, v234
	v_add_u32_e32 v66, 0xf9, v48
	v_cmp_lt_i32_e64 s[68:69], v66, v234
	v_add_u32_e32 v66, 0xfa, v48
	v_add_u32_e32 v48, 0xfb, v48
	v_cmp_lt_i32_e64 s[70:71], v66, v234
	v_cmp_lt_i32_e64 s[72:73], v48, v234
	s_or_b64 s[70:71], s[72:73], s[70:71]
	s_or_b64 s[68:69], s[70:71], s[68:69]
	s_or_b64 s[66:67], s[68:69], s[66:67]
	s_or_b64 s[64:65], s[66:67], s[64:65]
	s_or_b64 s[62:63], s[64:65], s[62:63]
	s_or_b64 s[60:61], s[62:63], s[60:61]
	s_or_b64 s[58:59], s[60:61], s[58:59]
	s_or_b64 s[56:57], s[58:59], s[56:57]
	s_or_b64 s[54:55], s[56:57], s[54:55]
	s_or_b64 s[52:53], s[54:55], s[52:53]
	s_or_b64 s[50:51], s[52:53], s[50:51]
	s_or_b64 s[44:45], s[50:51], s[44:45]
	s_or_b64 s[42:43], s[44:45], s[42:43]
	s_or_b64 s[0:1], s[42:43], s[0:1]
	s_or_b64 vcc, s[0:1], vcc
	v_cndmask_b32_e64 v61, 0, v61, s[72:73]
	v_cndmask_b32_e64 v60, 0, v60, s[70:71]
	v_cndmask_b32_e64 v55, 0, v55, s[68:69]
	v_cndmask_b32_e64 v54, 0, v54, s[66:67]
	v_cndmask_b32_e64 v43, 0, v43, s[64:65]
	v_cndmask_b32_e64 v42, 0, v42, s[62:63]
	v_cndmask_b32_e64 v41, 0, v41, s[60:61]
	v_cndmask_b32_e64 v40, 0, v40, s[58:59]
	v_cndmask_b32_e64 v39, 0, v39, s[56:57]
	v_cndmask_b32_e64 v38, 0, v38, s[54:55]
	v_cndmask_b32_e64 v37, 0, v37, s[52:53]
	v_cndmask_b32_e64 v36, 0, v36, s[50:51]
	v_cndmask_b32_e64 v35, 0, v35, s[44:45]
	v_cndmask_b32_e64 v34, 0, v34, s[42:43]
	v_cndmask_b32_e64 v33, 0, v33, s[0:1]
	v_cndmask_b32_e32 v32, 0, v32, vcc
	v_cndmask_b32_e32 v44, 1.0, v44, vcc
	v_cndmask_b32_e64 v45, 1.0, v45, s[0:1]
	v_cndmask_b32_e64 v46, 1.0, v46, s[42:43]
	v_cndmask_b32_e64 v47, 1.0, v47, s[44:45]
	v_cndmask_b32_e64 v50, 1.0, v50, s[50:51]
	v_cndmask_b32_e64 v51, 1.0, v51, s[52:53]
	v_cndmask_b32_e64 v52, 1.0, v52, s[54:55]
	v_cndmask_b32_e64 v53, 1.0, v53, s[56:57]
	v_cndmask_b32_e64 v56, 1.0, v56, s[58:59]
	v_cndmask_b32_e64 v57, 1.0, v57, s[60:61]
	v_cndmask_b32_e64 v58, 1.0, v58, s[62:63]
	v_cndmask_b32_e64 v59, 1.0, v59, s[64:65]
	v_cndmask_b32_e64 v62, 1.0, v62, s[66:67]
	v_cndmask_b32_e64 v63, 1.0, v63, s[68:69]
	v_cndmask_b32_e64 v64, 1.0, v64, s[70:71]
	v_cndmask_b32_e64 v65, 1.0, v65, s[72:73]
.LBB0_638:
	v_mov_b32_e32 v66, v45
	v_mov_b32_e32 v67, v46
	v_mov_b32_e32 v68, v44
	v_mov_b32_e32 v69, v47
	v_pk_mul_f32 v[66:67], v[66:67], v[68:69]
	v_mov_b32_e32 v68, v50
	v_mul_f32_e32 v44, v66, v67
	v_mov_b32_e32 v66, v51
	v_mov_b32_e32 v67, v52
	v_mov_b32_e32 v69, v53
	v_pk_mul_f32 v[66:67], v[66:67], v[68:69]
	v_mov_b32_e32 v68, v57
	v_mov_b32_e32 v69, v58
	v_mov_b32_e32 v70, v56
	v_mov_b32_e32 v71, v59
	v_pk_mul_f32 v[68:69], v[68:69], v[70:71]
	v_mov_b32_e32 v70, v63
	v_mov_b32_e32 v71, v64
	v_mov_b32_e32 v72, v62
	v_mov_b32_e32 v73, v65
	v_pk_mul_f32 v[70:71], v[70:71], v[72:73]
	v_mov_b32_e32 v48, v44
	v_mov_b32_e32 v50, v44
	v_pk_mul_f32 v[70:71], v[70:71], v[70:71] op_sel:[0,1] op_sel_hi:[1,0]
	s_nop 0
	v_permlane32_swap_b32_e32 v48, v50
	v_cndmask_b32_e64 v50, v48, v50, s[40:41]
	v_mov_b32_e32 v48, v70
	v_mov_b32_e32 v56, v70
	s_nop 1
	v_permlane32_swap_b32_e32 v48, v56
	v_cndmask_b32_e64 v71, v48, v56, s[40:41]
	v_cndmask_b32_e64 v48, 1.0, v71, s[40:41]
	v_mul_f32_e32 v48, v49, v48
	v_mul_f32_e32 v56, v65, v48
	v_mul_f32_e32 v62, v64, v56
	v_mul_f32_e32 v63, v63, v62
	v_mul_f32_e32 v56, v60, v56
	v_mul_f32_e32 v60, v55, v62
	v_mul_f32_e32 v62, v54, v63
	v_mov_b32_e32 v54, v68
	v_mov_b32_e32 v55, v70
	v_mov_b32_e32 v70, v69
	v_pk_mul_f32 v[54:55], v[54:55], v[70:71]
	v_mul_f32_e32 v61, v61, v48
	v_mov_b32_e32 v48, v54
	v_mov_b32_e32 v63, v54
	s_nop 1
	v_permlane32_swap_b32_e32 v48, v63
	v_cndmask_b32_e64 v48, v48, v63, s[40:41]
	v_cndmask_b32_e64 v63, 1.0, v48, s[40:41]
	v_pk_mul_f32 v[48:49], v[54:55], v[48:49]
	s_mov_b64 s[44:45], -1
	v_mul_f32_e32 v54, v63, v49
	v_mul_f32_e32 v55, v59, v54
	v_mul_f32_e32 v58, v58, v55
	v_mul_f32_e32 v57, v57, v58
	v_mul_f32_e32 v43, v43, v54
	v_mul_f32_e32 v42, v42, v55
	v_mul_f32_e32 v54, v41, v58
	v_mul_f32_e32 v55, v40, v57
	v_mov_b32_e32 v40, v66
	v_mov_b32_e32 v41, v48
	v_mov_b32_e32 v48, v67
	v_pk_mul_f32 v[40:41], v[40:41], v[48:49]
	s_mov_b64 s[34:35], 0
	v_mov_b32_e32 v48, v40
	v_mov_b32_e32 v49, v40
	s_nop 1
	v_permlane32_swap_b32_e32 v48, v49
	v_cndmask_b32_e64 v48, v48, v49, s[40:41]
	v_cndmask_b32_e64 v49, 1.0, v48, s[40:41]
	v_mul_f32_e32 v49, v49, v41
	v_mul_f32_e32 v53, v53, v49
	v_mul_f32_e32 v52, v52, v53
	v_mul_f32_e32 v51, v51, v52
	v_mul_f32_e32 v39, v39, v49
	v_mul_f32_e32 v49, v36, v51
	v_mul_f32_e32 v36, v40, v48
	v_mul_f32_e32 v36, v36, v41
	v_cndmask_b32_e64 v40, 1.0, v50, s[40:41]
	v_mul_f32_e32 v40, v40, v36
	v_mul_f32_e32 v41, v47, v40
	v_mul_f32_e32 v46, v46, v41
	v_mul_f32_e32 v45, v45, v46
	v_mul_f32_e32 v38, v38, v53
	v_mul_f32_e32 v35, v35, v40
	v_mul_f32_e32 v34, v34, v41
	v_mul_f32_e32 v33, v33, v46
	v_mul_f32_e32 v32, v32, v45
	v_mul_f32_e32 v37, v37, v52
	v_cvt_pk_bf16_f32 v32, v32, v33
	v_cvt_pk_bf16_f32 v33, v34, v35
	v_cvt_pk_bf16_f32 v34, v49, v37
	v_cvt_pk_bf16_f32 v35, v38, v39
	v_cvt_pk_bf16_f32 v38, v55, v54
	v_cvt_pk_bf16_f32 v39, v42, v43
	v_cvt_pk_bf16_f32 v40, v62, v60
	v_cvt_pk_bf16_f32 v41, v56, v61
	s_waitcnt lgkmcnt(0)
	s_nop 1
	v_mfma_f32_32x32x16_bf16 v[64:79], v[156:159], v[32:35], v[0:15]
	s_cmp_eq_u32 s29, -7
	s_mov_b64 s[0:1], 0
	s_mov_b64 s[42:43], -1
	v_mfma_f32_32x32x16_bf16 v[64:79], v[144:147], v[38:41], v[64:79]
	v_mfma_f32_32x32x16_bf16 v[80:95], v[136:139], v[32:35], v[16:31]
	v_mfma_f32_32x32x16_bf16 v[80:95], v[128:131], v[38:41], v[80:95]
	s_cbranch_scc1 .LBB0_631
; #define SBW_LOAD(j, KF, VR) do { const size_t kb_ = (size_t)(j) * 32; \
;         _Pragma("unroll") for (int s = 0; s < 4; ++s) KF[s] = *(const bf16x8*)(K + (kb_ + r32) * ld + s * 16 + hi * 8); \
;         _Pragma("unroll") for (int c4 = 0; c4 < 4; ++c4) VR[c4] = *(const u32x4*)(V + (kb_ + (lane >> 3) + 8 * c4) * ld + (lane & 7) * 8); } while (0)
; __device__ __forceinline__ void sb_wave_unit(const bf16_t* Q, const bf16_t* K, const bf16_t* V, int ld, bf16_t* O, int ldo, int q0, char* wl, int lane) {
;     ...
;         if (j < 2 || !__any(carry > 0.f)) break;
;         SBW_LOAD(SBW_CL(j - 4), kfB, vrB);
;         SBW_TILE(j - 2, kfC, vrC);
	v_mul_f32_e32 v32, v44, v50
	v_mul_f32_e32 v49, v32, v36
	v_cmp_lt_f32_e32 vcc, 0x2000, v49
	s_cbranch_vccz .LBB0_646
	s_min_u32 s0, s28, 4
	s_sub_i32 s0, s29, s0
	s_add_i32 s18, s0, 8
	s_lshl_b64 s[0:1], s[18:19], 5
	v_or_b32_e32 v32, s0, v212
	v_mad_u64_u32 v[32:33], s[42:43], v32, s78, v[228:229]
	v_mad_u32_u24 v33, s1, v242, v33
	global_load_dwordx4 v[156:159], v[32:33], off offset:2048
	global_load_dwordx4 v[144:147], v[32:33], off offset:2080
	global_load_dwordx4 v[136:139], v[32:33], off offset:2112
	global_load_dwordx4 v[128:131], v[32:33], off offset:2144
	v_or_b32_e32 v32, s0, v214
	v_mad_u64_u32 v[50:51], s[42:43], v32, s78, v[230:231]
	v_or_b32_e32 v48, s0, v216
	v_mad_u32_u24 v51, s1, v242, v51
	v_mad_u64_u32 v[52:53], s[42:43], v48, s78, v[230:231]
	v_or_b32_e32 v48, s0, v218
	v_mad_u32_u24 v53, s1, v242, v53
	global_load_dwordx4 v[164:167], v[50:51], off
	global_load_dwordx4 v[160:163], v[52:53], off
	v_mad_u64_u32 v[50:51], s[42:43], v48, s78, v[230:231]
	v_or_b32_e32 v48, s0, v220
	v_mad_u32_u24 v51, s1, v242, v51
	v_mad_u64_u32 v[52:53], s[42:43], v48, s78, v[230:231]
	v_mad_u32_u24 v53, s1, v242, v53
	global_load_dwordx4 v[172:175], v[50:51], off
	global_load_dwordx4 v[168:171], v[52:53], off
	v_mfma_f32_32x32x16_bf16 v[32:47], v[188:191], v[96:99], 0
	s_waitcnt lgkmcnt(0)
	s_addk_i32 s82, 0xdf
	s_cmp_lt_i32 s82, s39
	ds_write_b128 v211, v[192:195]
	ds_write_b128 v211, v[196:199] offset:512
	ds_write_b128 v211, v[204:207] offset:1024
	ds_write_b128 v211, v[200:203] offset:1536
	v_mfma_f32_32x32x16_bf16 v[32:47], v[184:187], v[100:103], v[32:47]
	v_mfma_f32_32x32x16_bf16 v[32:47], v[180:183], v[104:107], v[32:47]
	v_mfma_f32_32x32x16_bf16 v[32:47], v[176:179], v[108:111], v[32:47]
	s_nop 11
	v_mul_f32_e32 v44, 0xbe38aa3b, v44
	v_min_f32_e32 v44, 0x42c80000, v44
	v_mul_f32_e32 v32, 0xbe38aa3b, v32
	v_mul_f32_e32 v34, 0xbe38aa3b, v34
	v_mul_f32_e32 v36, 0xbe38aa3b, v36
	v_mul_f32_e32 v38, 0xbe38aa3b, v38
	v_mul_f32_e32 v40, 0xbe38aa3b, v40
	v_mul_f32_e32 v42, 0xbe38aa3b, v42
	v_exp_f32_e32 v178, v44
	v_mul_f32_e32 v44, 0xbe38aa3b, v45
	v_mul_f32_e32 v45, 0xbe38aa3b, v46
	v_min_f32_e32 v32, 0x42c80000, v32
	v_min_f32_e32 v34, 0x42c80000, v34
	v_min_f32_e32 v36, 0x42c80000, v36
	v_min_f32_e32 v38, 0x42c80000, v38
	v_min_f32_e32 v40, 0x42c80000, v40
	v_min_f32_e32 v42, 0x42c80000, v42
	v_min_f32_e32 v44, 0x42c80000, v44
	v_min_f32_e32 v45, 0x42c80000, v45
	v_exp_f32_e32 v50, v32
	v_mul_f32_e32 v32, 0xbe38aa3b, v33
	v_exp_f32_e32 v52, v34
	v_mul_f32_e32 v34, 0xbe38aa3b, v35
	v_exp_f32_e32 v56, v36
	v_mul_f32_e32 v36, 0xbe38aa3b, v37
	v_exp_f32_e32 v58, v38
	v_mul_f32_e32 v38, 0xbe38aa3b, v39
	v_exp_f32_e32 v62, v40
	v_mul_f32_e32 v40, 0xbe38aa3b, v41
	v_exp_f32_e32 v176, v42
	v_mul_f32_e32 v42, 0xbe38aa3b, v43
	v_exp_f32_e32 v179, v44
	v_exp_f32_e32 v180, v45
	v_mul_f32_e32 v45, 0xbe38aa3b, v47
	v_min_f32_e32 v32, 0x42c80000, v32
	v_min_f32_e32 v34, 0x42c80000, v34
	v_min_f32_e32 v36, 0x42c80000, v36
	v_min_f32_e32 v38, 0x42c80000, v38
	v_min_f32_e32 v40, 0x42c80000, v40
	v_min_f32_e32 v42, 0x42c80000, v42
	v_min_f32_e32 v45, 0x42c80000, v45
	v_exp_f32_e32 v51, v32
	v_exp_f32_e32 v53, v34
	v_exp_f32_e32 v57, v36
	v_exp_f32_e32 v59, v38
	v_exp_f32_e32 v63, v40
	v_exp_f32_e32 v177, v42
	v_exp_f32_e32 v181, v45
	v_add_f32_e32 v44, 1.0, v178
	v_rcp_f32_e32 v54, v44
	v_add_f32_e32 v44, 1.0, v179
	v_rcp_f32_e32 v55, v44
	v_add_f32_e32 v44, 1.0, v180
	v_add_f32_e32 v32, 1.0, v50
	v_add_f32_e32 v33, 1.0, v51
	v_add_f32_e32 v34, 1.0, v52
	v_add_f32_e32 v35, 1.0, v53
	v_add_f32_e32 v36, 1.0, v56
	v_add_f32_e32 v37, 1.0, v57
	v_add_f32_e32 v38, 1.0, v58
	v_add_f32_e32 v39, 1.0, v59
	v_add_f32_e32 v40, 1.0, v62
	v_add_f32_e32 v41, 1.0, v63
	v_add_f32_e32 v42, 1.0, v176
	v_add_f32_e32 v43, 1.0, v177
	v_rcp_f32_e32 v60, v44
	v_add_f32_e32 v44, 1.0, v181
	v_rcp_f32_e32 v32, v32
	v_rcp_f32_e32 v33, v33
	v_rcp_f32_e32 v34, v34
	v_rcp_f32_e32 v35, v35
	v_rcp_f32_e32 v36, v36
	v_rcp_f32_e32 v37, v37
	v_rcp_f32_e32 v38, v38
	v_rcp_f32_e32 v39, v39
	v_rcp_f32_e32 v40, v40
	v_rcp_f32_e32 v41, v41
	v_rcp_f32_e32 v42, v42
	v_rcp_f32_e32 v43, v43
	v_rcp_f32_e32 v61, v44
	v_pk_mul_f32 v[44:45], v[50:51], v[32:33]
	v_pk_mul_f32 v[46:47], v[52:53], v[34:35]
	v_pk_mul_f32 v[50:51], v[56:57], v[36:37]
	v_pk_mul_f32 v[52:53], v[58:59], v[38:39]
	v_pk_mul_f32 v[56:57], v[62:63], v[40:41]
	v_pk_mul_f32 v[58:59], v[176:177], v[42:43]
	v_pk_mul_f32 v[62:63], v[178:179], v[54:55]
	v_pk_mul_f32 v[176:177], v[180:181], v[60:61]
	s_cbranch_scc1 .LBB0_642
	v_add_u32_e32 v48, s48, v215
	v_add_u32_e32 v178, 0xc0, v48
	v_cmp_lt_i32_e32 vcc, v178, v234
	v_add_u32_e32 v178, 0xc1, v48
	v_cmp_lt_i32_e64 s[0:1], v178, v234
	v_add_u32_e32 v178, 0xc2, v48
	v_cmp_lt_i32_e64 s[42:43], v178, v234
	v_add_u32_e32 v178, 0xc3, v48
	v_cmp_lt_i32_e64 s[44:45], v178, v234
	v_add_u32_e32 v178, 0xc8, v48
	v_cmp_lt_i32_e64 s[50:51], v178, v234
	v_add_u32_e32 v178, 0xc9, v48
	v_cmp_lt_i32_e64 s[52:53], v178, v234
	v_add_u32_e32 v178, 0xca, v48
	v_cmp_lt_i32_e64 s[54:55], v178, v234
	v_add_u32_e32 v178, 0xcb, v48
	v_cmp_lt_i32_e64 s[56:57], v178, v234
	v_add_u32_e32 v178, 0xd0, v48
	v_cmp_lt_i32_e64 s[58:59], v178, v234
	v_add_u32_e32 v178, 0xd1, v48
	v_cmp_lt_i32_e64 s[60:61], v178, v234
	v_add_u32_e32 v178, 0xd2, v48
	v_cmp_lt_i32_e64 s[62:63], v178, v234
	v_add_u32_e32 v178, 0xd3, v48
	v_cmp_lt_i32_e64 s[64:65], v178, v234
	v_add_u32_e32 v178, 0xd8, v48
	v_cmp_lt_i32_e64 s[66:67], v178, v234
	v_add_u32_e32 v178, 0xd9, v48
	v_cmp_lt_i32_e64 s[68:69], v178, v234
	v_add_u32_e32 v178, 0xda, v48
	v_add_u32_e32 v48, 0xdb, v48
	v_cmp_lt_i32_e64 s[70:71], v178, v234
	v_cmp_lt_i32_e64 s[72:73], v48, v234
	s_or_b64 s[70:71], s[72:73], s[70:71]
	s_or_b64 s[68:69], s[70:71], s[68:69]
	s_or_b64 s[66:67], s[68:69], s[66:67]
	s_or_b64 s[64:65], s[66:67], s[64:65]
	s_or_b64 s[62:63], s[64:65], s[62:63]
	s_or_b64 s[60:61], s[62:63], s[60:61]
	s_or_b64 s[58:59], s[60:61], s[58:59]
	s_or_b64 s[56:57], s[58:59], s[56:57]
	s_or_b64 s[54:55], s[56:57], s[54:55]
	s_or_b64 s[52:53], s[54:55], s[52:53]
	s_or_b64 s[50:51], s[52:53], s[50:51]
	s_or_b64 s[44:45], s[50:51], s[44:45]
	s_or_b64 s[42:43], s[44:45], s[42:43]
	s_or_b64 s[0:1], s[42:43], s[0:1]
	s_or_b64 vcc, s[0:1], vcc
	v_cndmask_b32_e64 v61, 0, v61, s[72:73]
	v_cndmask_b32_e64 v60, 0, v60, s[70:71]
	v_cndmask_b32_e64 v55, 0, v55, s[68:69]
	v_cndmask_b32_e64 v54, 0, v54, s[66:67]
	v_cndmask_b32_e64 v43, 0, v43, s[64:65]
	v_cndmask_b32_e64 v42, 0, v42, s[62:63]
	v_cndmask_b32_e64 v41, 0, v41, s[60:61]
	v_cndmask_b32_e64 v40, 0, v40, s[58:59]
	v_cndmask_b32_e64 v39, 0, v39, s[56:57]
	v_cndmask_b32_e64 v38, 0, v38, s[54:55]
	v_cndmask_b32_e64 v37, 0, v37, s[52:53]
	v_cndmask_b32_e64 v36, 0, v36, s[50:51]
	v_cndmask_b32_e64 v35, 0, v35, s[44:45]
	v_cndmask_b32_e64 v34, 0, v34, s[42:43]
	v_cndmask_b32_e64 v33, 0, v33, s[0:1]
	v_cndmask_b32_e32 v32, 0, v32, vcc
	v_cndmask_b32_e32 v44, 1.0, v44, vcc
	v_cndmask_b32_e64 v45, 1.0, v45, s[0:1]
	v_cndmask_b32_e64 v46, 1.0, v46, s[42:43]
	v_cndmask_b32_e64 v47, 1.0, v47, s[44:45]
	v_cndmask_b32_e64 v50, 1.0, v50, s[50:51]
	v_cndmask_b32_e64 v51, 1.0, v51, s[52:53]
	v_cndmask_b32_e64 v52, 1.0, v52, s[54:55]
	v_cndmask_b32_e64 v53, 1.0, v53, s[56:57]
	v_cndmask_b32_e64 v56, 1.0, v56, s[58:59]
	v_cndmask_b32_e64 v57, 1.0, v57, s[60:61]
	v_cndmask_b32_e64 v58, 1.0, v58, s[62:63]
	v_cndmask_b32_e64 v59, 1.0, v59, s[64:65]
	v_cndmask_b32_e64 v62, 1.0, v62, s[66:67]
	v_cndmask_b32_e64 v63, 1.0, v63, s[68:69]
	v_cndmask_b32_e64 v176, 1.0, v176, s[70:71]
	v_cndmask_b32_e64 v177, 1.0, v177, s[72:73]
